# 3-buffer rotating prefetch, XCC_ID leader election, followers pace row loads by expert id against the leader clock
# speedup vs baseline: 1.1491x; 1.0309x over previous
_Z17hybrid_megakernel6Params:
	s_load_dwordx16 s[4:19], s[0:1], 0x0
	s_mov_b32 s60, s2
	v_and_b32_e32 v208, 0x3ff, v0
	v_or_b32_e32 v1, s60, v208
	v_cmp_eq_u32_e32 vcc, 0, v1
	s_waitcnt lgkmcnt(0)
	v_writelane_b32 v254, s4, 0
	s_nop 1
	v_writelane_b32 v254, s5, 1
	v_writelane_b32 v254, s6, 2
	v_writelane_b32 v254, s7, 3
	v_writelane_b32 v254, s8, 4
	v_writelane_b32 v254, s9, 5
	v_writelane_b32 v254, s10, 6
	v_writelane_b32 v254, s11, 7
	v_writelane_b32 v254, s12, 8
	v_writelane_b32 v254, s13, 9
	v_writelane_b32 v254, s14, 10
	v_writelane_b32 v254, s15, 11
	v_writelane_b32 v254, s16, 12
	v_writelane_b32 v254, s17, 13
	v_writelane_b32 v254, s18, 14
	v_writelane_b32 v254, s19, 15
	s_load_dwordx16 s[4:19], s[0:1], 0x40
	s_waitcnt lgkmcnt(0)
	v_writelane_b32 v254, s4, 16
	s_nop 1
	v_writelane_b32 v254, s5, 17
	v_writelane_b32 v254, s6, 18
	v_writelane_b32 v254, s7, 19
	v_writelane_b32 v254, s8, 20
	v_writelane_b32 v254, s9, 21
	v_writelane_b32 v254, s10, 22
	v_writelane_b32 v254, s11, 23
	v_writelane_b32 v254, s12, 24
	v_writelane_b32 v254, s13, 25
	v_writelane_b32 v254, s14, 26
	v_writelane_b32 v254, s15, 27
	v_writelane_b32 v254, s16, 28
	v_writelane_b32 v254, s17, 29
	v_writelane_b32 v254, s18, 30
	v_writelane_b32 v254, s19, 31
	s_load_dwordx2 s[92:93], s[0:1], 0x90
	s_load_dwordx4 s[4:7], s[0:1], 0x80
	s_load_dword s95, s[0:1], 0x98
	s_add_u32 s14, s0, 0x98
	s_addc_u32 s15, s1, 0
	s_waitcnt lgkmcnt(0)
	v_writelane_b32 v254, s4, 32
	s_nop 1
	v_writelane_b32 v254, s5, 33
	v_writelane_b32 v254, s6, 34
	v_writelane_b32 v254, s7, 35
	s_add_u32 s4, s92, 0x36f08000
	s_addc_u32 s5, s93, 0
	s_and_saveexec_b64 s[0:1], vcc
	s_cbranch_execz .LBB0_2
	v_mov_b32_e32 v1, 0
	global_store_dword v1, v1, s[4:5] sc1
	global_store_dword v1, v1, s[4:5] offset:2048 sc1
	global_store_dword v1, v1, s[4:5] offset:2176 sc1
	global_store_dword v1, v1, s[4:5] offset:2304 sc1
	global_store_dword v1, v1, s[4:5] offset:2432 sc1
	global_store_dword v1, v1, s[4:5] offset:2560 sc1
	global_store_dword v1, v1, s[4:5] offset:2688 sc1
	global_store_dword v1, v1, s[4:5] offset:2816 sc1
	global_store_dword v1, v1, s[4:5] offset:2944 sc1

.LBB0_598:
	s_barrier
	v_and_b32_e32 v249, 2, v60
	v_cmp_eq_u32_e64 s[6:7], 0, v249
	v_and_b32_e32 v249, 1, v60
	v_cmp_eq_u32_e64 s[0:1], 0, v249
	v_mov_b32_e32 v253, 0
	v_mov_b32_e32 v147, 0
	v_mov_b32_e32 v148, 0
	v_mov_b32_e32 v244, 0
	v_lshlrev_b32_e32 v248, 10, v58
	v_lshl_add_u32 v248, v60, 4, v248
	s_getreg_b32 s2, hwreg(HW_REG_XCC_ID)
	s_and_b32 s2, s2, 7
	s_lshl_b32 s2, s2, 7
	s_add_u32 s2, s2, s44
	s_addc_u32 s3, s45, 0
	s_add_u32 s2, s2, 0xffff8100
	s_addc_u32 s3, s3, -1
	v_mov_b32_e32 v246, s2
	v_mov_b32_e32 v247, s3
	v_mov_b32_e32 v250, 1
	s_mov_b64 exec, 1
	global_atomic_add v251, v[246:247], v250, off offset:1792 sc0
	s_mov_b64 exec, -1
	s_waitcnt vmcnt(0)
	v_readfirstlane_b32 s2, v251
	s_cmp_eq_u32 s2, 0
	s_cselect_b32 s82, 1, 0
	s_and_b32 s79, s2, 1
	s_lshl_b32 s79, s79, 10
	s_lshr_b32 s78, s2, 1
	s_and_b32 s78, s78, 0x7f
	s_add_i32 s78, s78, 768
	s_mov_b32 s23, 0
.Lxp_sweep:
	v_readfirstlane_b32 s2, v58
	s_lshr_b32 s3, s23, 2
	s_lshl_b32 s3, s3, 6
	s_add_i32 s2, s2, s3
	s_and_b32 s3, s23, 3
	s_lshl_b32 s3, s3, 2
	s_add_i32 s2, s2, s3
	s_add_i32 s2, s2, s34
	s_sub_i32 s32, s2, 64
	s_lshl_b32 s2, s32, 11
	s_add_u32 s36, s92, s2
	s_addc_u32 s37, s93, 0
	s_mov_b32 s25, 0
	v_mov_b32_e32 v243, 0
	v_mov_b32_e32 v253, 0

.Lxp_ukd:
	s_add_i32 s25, s25, 1
	s_cmp_lt_u32 s25, 4
	s_cbranch_scc1 .Lxp_tok
	s_waitcnt vmcnt(0)
	global_load_dword v70, v[246:247], off sc1
	ds_bpermute_b32 v64, v122, v240
	ds_bpermute_b32 v65, v122, v241
	s_mov_b32 vcc_lo, 0x99999999
	s_mov_b32 vcc_hi, 0x99999999
	s_waitcnt lgkmcnt(0)
	v_min_u32_e32 v66, v240, v64
	v_max_u32_e32 v67, v240, v64
	v_min_u32_e32 v68, v241, v65
	v_max_u32_e32 v69, v241, v65
	v_cndmask_b32_e32 v240, v67, v66, vcc
	v_cndmask_b32_e32 v241, v69, v68, vcc
	ds_bpermute_b32 v64, v123, v240
	ds_bpermute_b32 v65, v123, v241
	s_mov_b32 vcc_lo, 0xc3c3c3c3
	s_mov_b32 vcc_hi, 0xc3c3c3c3
	s_waitcnt lgkmcnt(0)
	v_min_u32_e32 v66, v240, v64
	v_max_u32_e32 v67, v240, v64
	v_min_u32_e32 v68, v241, v65
	v_max_u32_e32 v69, v241, v65
	v_cndmask_b32_e32 v240, v67, v66, vcc
	v_cndmask_b32_e32 v241, v69, v68, vcc
	ds_bpermute_b32 v64, v122, v240
	ds_bpermute_b32 v65, v122, v241
	s_mov_b32 vcc_lo, 0xa5a5a5a5
	s_mov_b32 vcc_hi, 0xa5a5a5a5
	s_waitcnt lgkmcnt(0)
	v_min_u32_e32 v66, v240, v64
	v_max_u32_e32 v67, v240, v64
	v_min_u32_e32 v68, v241, v65
	v_max_u32_e32 v69, v241, v65
	v_cndmask_b32_e32 v240, v67, v66, vcc
	v_cndmask_b32_e32 v241, v69, v68, vcc
	ds_bpermute_b32 v64, v124, v240
	ds_bpermute_b32 v65, v124, v241
	s_mov_b32 vcc_lo, 0xf00ff00f
	s_mov_b32 vcc_hi, 0xf00ff00f
	s_waitcnt lgkmcnt(0)
	v_min_u32_e32 v66, v240, v64
	v_max_u32_e32 v67, v240, v64
	v_min_u32_e32 v68, v241, v65
	v_max_u32_e32 v69, v241, v65
	v_cndmask_b32_e32 v240, v67, v66, vcc
	v_cndmask_b32_e32 v241, v69, v68, vcc
	ds_bpermute_b32 v64, v123, v240
	ds_bpermute_b32 v65, v123, v241
	s_mov_b32 vcc_lo, 0xcc33cc33
	s_mov_b32 vcc_hi, 0xcc33cc33
	s_waitcnt lgkmcnt(0)
	v_min_u32_e32 v66, v240, v64
	v_max_u32_e32 v67, v240, v64
	v_min_u32_e32 v68, v241, v65
	v_max_u32_e32 v69, v241, v65
	v_cndmask_b32_e32 v240, v67, v66, vcc
	v_cndmask_b32_e32 v241, v69, v68, vcc
	ds_bpermute_b32 v64, v122, v240
	ds_bpermute_b32 v65, v122, v241
	s_mov_b32 vcc_lo, 0xaa55aa55
	s_mov_b32 vcc_hi, 0xaa55aa55
	s_waitcnt lgkmcnt(0)
	v_min_u32_e32 v66, v240, v64
	v_max_u32_e32 v67, v240, v64
	v_min_u32_e32 v68, v241, v65
	v_max_u32_e32 v69, v241, v65
	v_cndmask_b32_e32 v240, v67, v66, vcc
	v_cndmask_b32_e32 v241, v69, v68, vcc
	ds_bpermute_b32 v64, v125, v240
	ds_bpermute_b32 v65, v125, v241
	s_mov_b32 vcc_lo, 0xff0000ff
	s_mov_b32 vcc_hi, 0xff0000ff
	s_waitcnt lgkmcnt(0)
	v_min_u32_e32 v66, v240, v64
	v_max_u32_e32 v67, v240, v64
	v_min_u32_e32 v68, v241, v65
	v_max_u32_e32 v69, v241, v65
	v_cndmask_b32_e32 v240, v67, v66, vcc
	v_cndmask_b32_e32 v241, v69, v68, vcc
	ds_bpermute_b32 v64, v124, v240
	ds_bpermute_b32 v65, v124, v241
	s_mov_b32 vcc_lo, 0xf0f00f0f
	s_mov_b32 vcc_hi, 0xf0f00f0f
	s_waitcnt lgkmcnt(0)
	v_min_u32_e32 v66, v240, v64
	v_max_u32_e32 v67, v240, v64
	v_min_u32_e32 v68, v241, v65
	v_max_u32_e32 v69, v241, v65
	v_cndmask_b32_e32 v240, v67, v66, vcc
	v_cndmask_b32_e32 v241, v69, v68, vcc
	ds_bpermute_b32 v64, v123, v240
	ds_bpermute_b32 v65, v123, v241
	s_mov_b32 vcc_lo, 0xcccc3333
	s_mov_b32 vcc_hi, 0xcccc3333
	s_waitcnt lgkmcnt(0)
	v_min_u32_e32 v66, v240, v64
	v_max_u32_e32 v67, v240, v64
	v_min_u32_e32 v68, v241, v65
	v_max_u32_e32 v69, v241, v65
	v_cndmask_b32_e32 v240, v67, v66, vcc
	v_cndmask_b32_e32 v241, v69, v68, vcc
	ds_bpermute_b32 v64, v122, v240
	ds_bpermute_b32 v65, v122, v241
	s_mov_b32 vcc_lo, 0xaaaa5555
	s_mov_b32 vcc_hi, 0xaaaa5555
	s_waitcnt lgkmcnt(0)
	v_min_u32_e32 v66, v240, v64
	v_max_u32_e32 v67, v240, v64
	v_min_u32_e32 v68, v241, v65
	v_max_u32_e32 v69, v241, v65
	v_cndmask_b32_e32 v240, v67, v66, vcc
	v_cndmask_b32_e32 v241, v69, v68, vcc
	ds_bpermute_b32 v64, v126, v240
	ds_bpermute_b32 v65, v126, v241
	s_mov_b32 vcc_lo, 0x0000ffff
	s_mov_b32 vcc_hi, 0xffff0000
	s_waitcnt lgkmcnt(0)
	v_min_u32_e32 v66, v240, v64
	v_max_u32_e32 v67, v240, v64
	v_min_u32_e32 v68, v241, v65
	v_max_u32_e32 v69, v241, v65
	v_cndmask_b32_e32 v240, v67, v66, vcc
	v_cndmask_b32_e32 v241, v69, v68, vcc
	ds_bpermute_b32 v64, v125, v240
	ds_bpermute_b32 v65, v125, v241
	s_mov_b32 vcc_lo, 0x00ff00ff
	s_mov_b32 vcc_hi, 0xff00ff00
	s_waitcnt lgkmcnt(0)
	v_min_u32_e32 v66, v240, v64
	v_max_u32_e32 v67, v240, v64
	v_min_u32_e32 v68, v241, v65
	v_max_u32_e32 v69, v241, v65
	v_cndmask_b32_e32 v240, v67, v66, vcc
	v_cndmask_b32_e32 v241, v69, v68, vcc
	ds_bpermute_b32 v64, v124, v240
	ds_bpermute_b32 v65, v124, v241
	s_mov_b32 vcc_lo, 0x0f0f0f0f
	s_mov_b32 vcc_hi, 0xf0f0f0f0
	s_waitcnt lgkmcnt(0)
	v_min_u32_e32 v66, v240, v64
	v_max_u32_e32 v67, v240, v64
	v_min_u32_e32 v68, v241, v65
	v_max_u32_e32 v69, v241, v65
	v_cndmask_b32_e32 v240, v67, v66, vcc
	v_cndmask_b32_e32 v241, v69, v68, vcc
	ds_bpermute_b32 v64, v123, v240
	ds_bpermute_b32 v65, v123, v241
	s_mov_b32 vcc_lo, 0x33333333
	s_mov_b32 vcc_hi, 0xcccccccc
	s_waitcnt lgkmcnt(0)
	v_min_u32_e32 v66, v240, v64
	v_max_u32_e32 v67, v240, v64
	v_min_u32_e32 v68, v241, v65
	v_max_u32_e32 v69, v241, v65
	v_cndmask_b32_e32 v240, v67, v66, vcc
	v_cndmask_b32_e32 v241, v69, v68, vcc
	ds_bpermute_b32 v64, v122, v240
	ds_bpermute_b32 v65, v122, v241
	s_mov_b32 vcc_lo, 0x55555555
	s_mov_b32 vcc_hi, 0xaaaaaaaa
	s_waitcnt lgkmcnt(0)
	v_min_u32_e32 v66, v240, v64
	v_max_u32_e32 v67, v240, v64
	v_min_u32_e32 v68, v241, v65
	v_max_u32_e32 v69, v241, v65
	v_cndmask_b32_e32 v240, v67, v66, vcc
	v_cndmask_b32_e32 v241, v69, v68, vcc
	ds_bpermute_b32 v64, v127, v240
	ds_bpermute_b32 v65, v127, v241
	s_mov_b32 vcc_lo, 0xffffffff
	s_mov_b32 vcc_hi, 0x00000000
	s_waitcnt lgkmcnt(0)
	v_min_u32_e32 v66, v240, v64
	v_max_u32_e32 v67, v240, v64
	v_min_u32_e32 v68, v241, v65
	v_max_u32_e32 v69, v241, v65
	v_cndmask_b32_e32 v240, v67, v66, vcc
	v_cndmask_b32_e32 v241, v68, v69, vcc
	ds_bpermute_b32 v64, v126, v240
	ds_bpermute_b32 v65, v126, v241
	s_mov_b32 vcc_lo, 0x0000ffff
	s_mov_b32 vcc_hi, 0x0000ffff
	s_waitcnt lgkmcnt(0)
	v_min_u32_e32 v66, v240, v64
	v_max_u32_e32 v67, v240, v64
	v_min_u32_e32 v68, v241, v65
	v_max_u32_e32 v69, v241, v65
	v_cndmask_b32_e32 v240, v67, v66, vcc
	v_cndmask_b32_e32 v241, v68, v69, vcc
	ds_bpermute_b32 v64, v125, v240
	ds_bpermute_b32 v65, v125, v241
	s_mov_b32 vcc_lo, 0x00ff00ff
	s_mov_b32 vcc_hi, 0x00ff00ff
	s_waitcnt lgkmcnt(0)
	v_min_u32_e32 v66, v240, v64
	v_max_u32_e32 v67, v240, v64
	v_min_u32_e32 v68, v241, v65
	v_max_u32_e32 v69, v241, v65
	v_cndmask_b32_e32 v240, v67, v66, vcc
	v_cndmask_b32_e32 v241, v68, v69, vcc
	ds_bpermute_b32 v64, v124, v240
	ds_bpermute_b32 v65, v124, v241
	s_mov_b32 vcc_lo, 0x0f0f0f0f
	s_mov_b32 vcc_hi, 0x0f0f0f0f
	s_waitcnt lgkmcnt(0)
	v_min_u32_e32 v66, v240, v64
	v_max_u32_e32 v67, v240, v64
	v_min_u32_e32 v68, v241, v65
	v_max_u32_e32 v69, v241, v65
	v_cndmask_b32_e32 v240, v67, v66, vcc
	v_cndmask_b32_e32 v241, v68, v69, vcc
	ds_bpermute_b32 v64, v123, v240
	ds_bpermute_b32 v65, v123, v241
	s_mov_b32 vcc_lo, 0x33333333
	s_mov_b32 vcc_hi, 0x33333333
	s_waitcnt lgkmcnt(0)
	v_min_u32_e32 v66, v240, v64
	v_max_u32_e32 v67, v240, v64
	v_min_u32_e32 v68, v241, v65
	v_max_u32_e32 v69, v241, v65
	v_cndmask_b32_e32 v240, v67, v66, vcc
	v_cndmask_b32_e32 v241, v68, v69, vcc
	ds_bpermute_b32 v64, v122, v240
	ds_bpermute_b32 v65, v122, v241
	s_mov_b32 vcc_lo, 0x55555555
	s_mov_b32 vcc_hi, 0x55555555
	s_waitcnt lgkmcnt(0)
	v_min_u32_e32 v66, v240, v64
	v_max_u32_e32 v67, v240, v64
	v_min_u32_e32 v68, v241, v65
	v_max_u32_e32 v69, v241, v65
	v_cndmask_b32_e32 v240, v67, v66, vcc
	v_cndmask_b32_e32 v241, v68, v69, vcc
	v_min_u32_e32 v66, v240, v241
	v_max_u32_e32 v241, v240, v241
	v_mov_b32_e32 v240, v66
	ds_bpermute_b32 v64, v127, v240
	ds_bpermute_b32 v65, v127, v241
	s_mov_b32 vcc_lo, 0xffffffff
	s_mov_b32 vcc_hi, 0x00000000
	s_waitcnt lgkmcnt(0)
	v_min_u32_e32 v66, v240, v64
	v_max_u32_e32 v67, v240, v64
	v_min_u32_e32 v68, v241, v65
	v_max_u32_e32 v69, v241, v65
	v_cndmask_b32_e32 v240, v67, v66, vcc
	v_cndmask_b32_e32 v241, v69, v68, vcc
	ds_bpermute_b32 v64, v126, v240
	ds_bpermute_b32 v65, v126, v241
	s_mov_b32 vcc_lo, 0x0000ffff
	s_mov_b32 vcc_hi, 0x0000ffff
	s_waitcnt lgkmcnt(0)
	v_min_u32_e32 v66, v240, v64
	v_max_u32_e32 v67, v240, v64
	v_min_u32_e32 v68, v241, v65
	v_max_u32_e32 v69, v241, v65
	v_cndmask_b32_e32 v240, v67, v66, vcc
	v_cndmask_b32_e32 v241, v69, v68, vcc
	ds_bpermute_b32 v64, v125, v240
	ds_bpermute_b32 v65, v125, v241
	s_mov_b32 vcc_lo, 0x00ff00ff
	s_mov_b32 vcc_hi, 0x00ff00ff
	s_waitcnt lgkmcnt(0)
	v_min_u32_e32 v66, v240, v64
	v_max_u32_e32 v67, v240, v64
	v_min_u32_e32 v68, v241, v65
	v_max_u32_e32 v69, v241, v65
	v_cndmask_b32_e32 v240, v67, v66, vcc
	v_cndmask_b32_e32 v241, v69, v68, vcc
	ds_bpermute_b32 v64, v124, v240
	ds_bpermute_b32 v65, v124, v241
	s_mov_b32 vcc_lo, 0x0f0f0f0f
	s_mov_b32 vcc_hi, 0x0f0f0f0f
	s_waitcnt lgkmcnt(0)
	v_min_u32_e32 v66, v240, v64
	v_max_u32_e32 v67, v240, v64
	v_min_u32_e32 v68, v241, v65
	v_max_u32_e32 v69, v241, v65
	v_cndmask_b32_e32 v240, v67, v66, vcc
	v_cndmask_b32_e32 v241, v69, v68, vcc
	ds_bpermute_b32 v64, v123, v240
	ds_bpermute_b32 v65, v123, v241
	s_mov_b32 vcc_lo, 0x33333333
	s_mov_b32 vcc_hi, 0x33333333
	s_waitcnt lgkmcnt(0)
	v_min_u32_e32 v66, v240, v64
	v_max_u32_e32 v67, v240, v64
	v_min_u32_e32 v68, v241, v65
	v_max_u32_e32 v69, v241, v65
	v_cndmask_b32_e32 v240, v67, v66, vcc
	v_cndmask_b32_e32 v241, v69, v68, vcc
	ds_bpermute_b32 v64, v122, v240
	ds_bpermute_b32 v65, v122, v241
	s_mov_b32 vcc_lo, 0x55555555
	s_mov_b32 vcc_hi, 0x55555555
	s_waitcnt lgkmcnt(0)
	v_min_u32_e32 v66, v240, v64
	v_max_u32_e32 v67, v240, v64
	v_min_u32_e32 v68, v241, v65
	v_max_u32_e32 v69, v241, v65
	v_cndmask_b32_e32 v240, v67, v66, vcc
	v_cndmask_b32_e32 v241, v69, v68, vcc
	s_waitcnt vmcnt(0)
	v_readfirstlane_b32 s2, v70
	s_and_b32 s2, s2, 0x3fff
	s_mov_b32 s97, s2
	s_lshl_b32 s3, s2, 7
	v_cmp_gt_u32_e32 vcc, s3, v240
	s_nop 1
	s_bcnt1_i32_b64 s2, vcc
	v_cmp_gt_u32_e32 vcc, s3, v241
	s_nop 1
	s_bcnt1_i32_b64 s3, vcc
	s_add_i32 s2, s2, s3
	v_add_u32_e32 v64, s2, v60
	v_and_b32_e32 v64, 0x7f, v64
	v_and_b32_e32 v65, 63, v64
	v_lshlrev_b32_e32 v65, 2, v65
	ds_bpermute_b32 v66, v65, v240
	ds_bpermute_b32 v67, v65, v241
	v_cmp_gt_u32_e32 vcc, 64, v64
	s_waitcnt lgkmcnt(0)
	v_cndmask_b32_e32 v240, v67, v66, vcc
	v_cndmask_b32_e32 v241, v66, v67, vcc
	v_mov_b32_e32 v132, v70
	s_nop 1
	v_readlane_b32 s2, v240, 0
	s_and_b32 s3, s2, 31
	s_lshl_b32 s3, s3, 5
	s_bfe_u32 s94, s2, 0x20005
	s_lshl_b32 s2, s94, 11
	s_add_i32 s3, s3, s2
	s_load_dwordx8 s[84:91], s[36:37], s3
	s_waitcnt lgkmcnt(0)
	s_and_b32 s84, s84, 0x3fff
	s_lshl_b32 s2, s84, 11
	v_lshl_add_u32 v249, v60, 4, s2
	global_load_dwordx4 v[8:11], v249, s[18:19]
	global_load_dwordx4 v[40:43], v249, s[20:21]
	s_lshl_b32 s2, s84, 2
	v_writelane_b32 v147, s2, 0
	v_writelane_b32 v0, s85, 0
	s_and_b32 s86, s86, 0x3fff
	s_lshl_b32 s2, s86, 11
	v_lshl_add_u32 v249, v60, 4, s2
	global_load_dwordx4 v[16:19], v249, s[18:19]
	global_load_dwordx4 v[44:47], v249, s[20:21]
	s_lshl_b32 s2, s86, 2
	v_writelane_b32 v147, s2, 1
	v_writelane_b32 v0, s87, 1
	s_and_b32 s88, s88, 0x3fff
	s_lshl_b32 s2, s88, 11
	v_lshl_add_u32 v249, v60, 4, s2
	global_load_dwordx4 v[32:35], v249, s[18:19]
	global_load_dwordx4 v[48:51], v249, s[20:21]
	s_lshl_b32 s2, s88, 2
	v_writelane_b32 v147, s2, 2
	v_writelane_b32 v0, s89, 2
	s_and_b32 s90, s90, 0x3fff
	s_lshl_b32 s2, s90, 11
	v_lshl_add_u32 v249, v60, 4, s2
	global_load_dwordx4 v[36:39], v249, s[18:19]
	global_load_dwordx4 v[52:55], v249, s[20:21]
	s_lshl_b32 s2, s90, 2
	v_writelane_b32 v147, s2, 3
	v_writelane_b32 v0, s91, 3
	global_load_dword v138, v147, s[44:45]
	global_load_dword v139, v147, s[46:47]
	s_mov_b32 s33, s94
	v_readlane_b32 s2, v240, 1
	s_and_b32 s3, s2, 31
	s_lshl_b32 s3, s3, 5
	s_bfe_u32 s94, s2, 0x20005
	s_lshl_b32 s2, s94, 11
	s_add_i32 s3, s3, s2
	s_load_dwordx8 s[84:91], s[36:37], s3
	s_waitcnt lgkmcnt(0)
	s_and_b32 s84, s84, 0x3fff
	s_lshl_b32 s2, s84, 11
	v_lshl_add_u32 v249, v60, 4, s2
	global_load_dwordx4 v[152:155], v249, s[18:19]
	global_load_dwordx4 v[12:15], v249, s[20:21]
	s_lshl_b32 s2, s84, 2
	v_writelane_b32 v147, s2, 0
	v_writelane_b32 v1, s85, 0
	s_and_b32 s86, s86, 0x3fff
	s_lshl_b32 s2, s86, 11
	v_lshl_add_u32 v249, v60, 4, s2
	global_load_dwordx4 v[156:159], v249, s[18:19]
	global_load_dwordx4 v[20:23], v249, s[20:21]
	s_lshl_b32 s2, s86, 2
	v_writelane_b32 v147, s2, 1
	v_writelane_b32 v1, s87, 1
	s_and_b32 s88, s88, 0x3fff
	s_lshl_b32 s2, s88, 11
	v_lshl_add_u32 v249, v60, 4, s2
	global_load_dwordx4 v[160:163], v249, s[18:19]
	global_load_dwordx4 v[24:27], v249, s[20:21]
	s_lshl_b32 s2, s88, 2
	v_writelane_b32 v147, s2, 2
	v_writelane_b32 v1, s89, 2
	s_and_b32 s90, s90, 0x3fff
	s_lshl_b32 s2, s90, 11
	v_lshl_add_u32 v249, v60, 4, s2
	global_load_dwordx4 v[164:167], v249, s[18:19]
	global_load_dwordx4 v[28:31], v249, s[20:21]
	s_lshl_b32 s2, s90, 2
	v_writelane_b32 v147, s2, 3
	v_writelane_b32 v1, s91, 3
	global_load_dword v140, v147, s[44:45]
	global_load_dword v141, v147, s[46:47]
	s_mov_b32 s80, s94
	v_readlane_b32 s2, v240, 2
	s_and_b32 s3, s2, 31
	s_lshl_b32 s3, s3, 5
	s_bfe_u32 s94, s2, 0x20005
	s_lshl_b32 s2, s94, 11
	s_add_i32 s3, s3, s2
	s_load_dwordx8 s[84:91], s[36:37], s3
	s_mov_b32 s81, s94
	v_mov_b32_e32 v90, 0
	v_mov_b32_e32 v91, 0
	v_mov_b32_e32 v92, 0
	v_mov_b32_e32 v93, 0
	v_mov_b32_e32 v94, 0
	v_mov_b32_e32 v95, 0
	v_mov_b32_e32 v96, 0
	v_mov_b32_e32 v97, 0
	v_mov_b32_e32 v98, 0
	v_mov_b32_e32 v99, 0
	v_mov_b32_e32 v100, 0
	v_mov_b32_e32 v101, 0
	v_mov_b32_e32 v102, 0
	v_mov_b32_e32 v103, 0
	v_mov_b32_e32 v104, 0
	v_mov_b32_e32 v105, 0
	v_mov_b32_e32 v142, 0
	v_readlane_b32 s3, v244, s33
	s_nop 1
	v_mov_b32_e32 v137, s3
	s_cmp_eq_u32 s33, 0
	s_cbranch_scc1 .Lxp_ixq0
	s_cmp_eq_u32 s33, 1
	s_cbranch_scc1 .Lxp_ixq1
	s_cmp_eq_u32 s33, 2
	s_cbranch_scc1 .Lxp_ixq2
	v_mov_b32_e32 v133, v236
	v_mov_b32_e32 v134, v237
	v_mov_b32_e32 v135, v238
	v_mov_b32_e32 v136, v239
	s_branch .Lxp_ixqd

.Lxp_ixqd:
	s_mov_b32 s25, 0
	s_waitcnt vmcnt(10)
.Lxp_unit:
	s_cmp_eq_u32 s82, 1
	s_cbranch_scc0 .Lxp_fola
	s_lshl_b32 s2, s25, 7
	s_add_i32 s2, s2, s97
	s_and_b32 s2, s2, 0x3fff
	v_mov_b32_e32 v245, s2
	s_mov_b64 exec, 1
	global_store_dword v[246:247], v245, off
	s_mov_b64 exec, -1
	s_sleep 3
	s_waitcnt lgkmcnt(0)
	s_branch .Lxp_syncda
.Lxp_fola:
	s_waitcnt lgkmcnt(0)
	v_readfirstlane_b32 s2, v132
	s_mov_b32 vcc_lo, 16
	s_and_b32 s83, s84, 0x3fff
.Lxp_chka:
	s_bitcmp1_b32 s2, 31
	s_cbranch_scc1 .Lxp_goa
	s_sub_i32 s3, s83, s2
	s_and_b32 s3, s3, 0x3fff
	s_cmp_lt_u32 s3, 0x2000
	s_cbranch_scc0 .Lxp_goa
	s_cmp_gt_u32 s3, 0x180
	s_cbranch_scc0 .Lxp_goa
	s_sub_i32 vcc_lo, vcc_lo, 1
	s_cmp_eq_u32 vcc_lo, 0
	s_cbranch_scc1 .Lxp_goa
	s_sleep 8
	global_load_dword v132, v[246:247], off sc1
	s_waitcnt vmcnt(0)
	v_readfirstlane_b32 s2, v132
	s_branch .Lxp_chka
.Lxp_goa:
	global_load_dword v132, v[246:247], off sc1
.Lxp_syncda:
	s_and_b32 s84, s84, 0x3fff
	s_lshl_b32 s2, s84, 11
	v_lshl_add_u32 v249, v60, 4, s2
	global_load_dwordx4 v[72:75], v249, s[18:19]
	global_load_dwordx4 v[64:67], v249, s[20:21]
	s_lshl_b32 s2, s84, 2
	v_writelane_b32 v147, s2, 0
	v_writelane_b32 v2, s85, 0
	s_and_b32 s86, s86, 0x3fff
	s_lshl_b32 s2, s86, 11
	v_lshl_add_u32 v249, v60, 4, s2
	global_load_dwordx4 v[76:79], v249, s[18:19]
	global_load_dwordx4 v[68:71], v249, s[20:21]
	s_lshl_b32 s2, s86, 2
	v_writelane_b32 v147, s2, 1
	v_writelane_b32 v2, s87, 1
	s_and_b32 s88, s88, 0x3fff
	s_lshl_b32 s2, s88, 11
	v_lshl_add_u32 v249, v60, 4, s2
	global_load_dwordx4 v[80:83], v249, s[18:19]
	global_load_dwordx4 v[4:7], v249, s[20:21]
	s_lshl_b32 s2, s88, 2
	v_writelane_b32 v147, s2, 2
	v_writelane_b32 v2, s89, 2
	s_and_b32 s90, s90, 0x3fff
	s_lshl_b32 s2, s90, 11
	v_lshl_add_u32 v249, v60, 4, s2
	global_load_dwordx4 v[84:87], v249, s[18:19]
	global_load_dwordx4 v[128:131], v249, s[20:21]
	s_lshl_b32 s2, s90, 2
	v_writelane_b32 v147, s2, 3
	v_writelane_b32 v2, s91, 3
	global_load_dword v88, v147, s[44:45]
	global_load_dword v89, v147, s[46:47]
	s_add_i32 s3, s25, 3
	s_min_u32 s3, s3, 0x7f
	s_cmp_lt_u32 s3, 64
	s_cselect_b64 vcc, -1, 0
	s_nop 0
	v_cndmask_b32_e32 v249, v241, v240, vcc
	s_nop 1
	v_readlane_b32 s2, v249, s3
	s_and_b32 s3, s2, 31
	s_lshl_b32 s3, s3, 5
	s_bfe_u32 s94, s2, 0x20005
	s_lshl_b32 s2, s94, 11
	s_add_i32 s3, s3, s2
	s_load_dwordx8 s[84:91], s[36:37], s3
	v_mov_b32_e32 v149, 0
	v_mov_b32_e32 v150, 0
	v_mov_b32_e32 v151, 0
	v_mov_b32_e32 v148, 0
	v_dot4c_i32_i8_e32 v149, v8, v133
	v_dot4c_i32_i8_e32 v150, v16, v133
	v_dot4c_i32_i8_e32 v151, v32, v133
	v_dot4c_i32_i8_e32 v148, v36, v133
	v_dot4c_i32_i8_e32 v149, v9, v134
	v_dot4c_i32_i8_e32 v150, v17, v134
	v_dot4c_i32_i8_e32 v151, v33, v134
	v_dot4c_i32_i8_e32 v148, v37, v134
	v_dot4c_i32_i8_e32 v149, v10, v135
	v_dot4c_i32_i8_e32 v150, v18, v135
	v_dot4c_i32_i8_e32 v151, v34, v135
	v_dot4c_i32_i8_e32 v148, v38, v135
	v_dot4c_i32_i8_e32 v149, v11, v136
	v_dot4c_i32_i8_e32 v150, v19, v136
	v_dot4c_i32_i8_e32 v151, v35, v136
	v_dot4c_i32_i8_e32 v148, v39, v136
	s_nop 3
	v_cndmask_b32_e64 v143, v149, v150, s[0:1]
	v_cndmask_b32_e64 v144, v150, v149, s[0:1]
	v_cndmask_b32_e64 v145, v151, v148, s[0:1]
	v_cndmask_b32_e64 v146, v148, v151, s[0:1]
	s_nop 1
	v_add_u32_dpp v144, v143, v144 quad_perm:[1,0,3,2] row_mask:0xf bank_mask:0xf
	v_add_u32_dpp v146, v145, v146 quad_perm:[1,0,3,2] row_mask:0xf bank_mask:0xf
	s_nop 1
	v_cndmask_b32_e64 v143, v144, v146, s[6:7]
	v_cndmask_b32_e64 v145, v146, v144, s[6:7]
	s_nop 1
	v_add_u32_dpp v145, v143, v145 quad_perm:[2,3,0,1] row_mask:0xf bank_mask:0xf
	s_nop 1
	v_add_u32_dpp v145, v145, v145 row_ror:4 row_mask:0xf bank_mask:0xf
	s_nop 1
	v_add_u32_dpp v145, v145, v145 row_ror:8 row_mask:0xf bank_mask:0xf
	s_nop 1
	ds_bpermute_b32 v143, v126, v145
	s_waitcnt lgkmcnt(0)
	v_add_u32_e32 v145, v145, v143
	ds_bpermute_b32 v143, v127, v145
	s_waitcnt lgkmcnt(0)
	v_add_u32_e32 v145, v145, v143
	v_cvt_f32_i32_e32 v56, v145
	v_mul_f32_e32 v59, v138, v56
	v_mul_f32_e32 v59, v137, v59
	v_mul_f32_e32 v56, 0x3f3504f3, v59
	v_fma_f32 v143, |v56|, s66, v120
	v_fma_f32 v143, |v56|, v143, s67
	v_fma_f32 v143, |v56|, v143, s68
	v_fma_f32 v143, |v56|, v143, s69
	v_fma_f32 v143, |v56|, v143, s70
	v_fma_f32 v143, |v56|, v143, s71
	v_fma_f32 v143, |v56|, v143, |v56|
	v_mul_f32_e32 v144, 0xbfb8aa3b, v143
	v_fma_f32 v146, v143, s72, -v144
	v_rndne_f32_e32 v3, v144
	v_fmac_f32_e32 v146, 0xb2a5705f, v143
	v_sub_f32_e32 v144, v144, v3
	v_add_f32_e32 v144, v144, v146
	v_cvt_i32_f32_e32 v146, v3
	v_exp_f32_e32 v144, v144
	v_cmp_nlt_f32_e32 vcc, s73, v143
	v_ldexp_f32 v144, v144, v146
	s_nop 0
	v_cndmask_b32_e32 v144, 0, v144, vcc
	v_cmp_ngt_f32_e32 vcc, s74, v143
	s_nop 1
	v_cndmask_b32_e32 v143, v121, v144, vcc
	v_sub_f32_e32 v143, 1.0, v143
	v_mul_f32_e32 v168, v56, v56
	v_fmamk_f32 v169, v168, 0xba1345e1, v117
	v_fmaak_f32 v169, v168, v169, 0xbcdac9b8
	v_fmaak_f32 v169, v168, v169, 0x3de703be
	v_fmaak_f32 v169, v168, v169, 0xbec09330
	v_fmaak_f32 v168, v168, v169, 0x3e0375d0
	v_fma_f32 v168, |v56|, v168, |v56|
	v_cmp_nlt_f32_e64 vcc, |v56|, 1.0
	s_nop 1
	v_cndmask_b32_e32 v143, v168, v143, vcc
	v_bfi_b32 v146, s75, v143, v56
	v_mul_f32_e32 v145, 0.5, v59
	v_add_f32_e32 v146, 1.0, v146
	v_mul_f32_e32 v145, v145, v146
	v_mul_f32_e32 v144, v0, v145
	v_mul_f32_e32 v143, v139, v144
	s_nop 1
	v_readlane_b32 s40, v143, 0
	v_readlane_b32 s38, v143, 1
	v_readlane_b32 s42, v143, 2
	v_readlane_b32 s2, v143, 3
	s_nop 1
	v_add_f32_e32 v142, s40, v142
	v_add_f32_e32 v142, s38, v142
	v_add_f32_e32 v142, s42, v142
	v_add_f32_e32 v142, s2, v142
	v_cvt_f32_ubyte1_e32 v169, v40
	v_cvt_f32_ubyte0_e32 v168, v40
	v_pk_fma_f32 v[104:105], s[40:41], v[168:169], v[104:105] op_sel_hi:[0,1,1]
	v_cvt_f32_ubyte1_e32 v171, v44
	v_cvt_f32_ubyte0_e32 v170, v44
	v_pk_fma_f32 v[104:105], s[38:39], v[170:171], v[104:105] op_sel_hi:[0,1,1]
	v_cvt_f32_ubyte1_e32 v169, v48
	v_cvt_f32_ubyte0_e32 v168, v48
	v_pk_fma_f32 v[104:105], s[42:43], v[168:169], v[104:105] op_sel_hi:[0,1,1]
	v_cvt_f32_ubyte1_e32 v171, v52
	v_cvt_f32_ubyte0_e32 v170, v52
	v_pk_fma_f32 v[104:105], s[2:3], v[170:171], v[104:105] op_sel_hi:[0,1,1]
	v_cvt_f32_ubyte3_e32 v169, v40
	v_cvt_f32_ubyte2_e32 v168, v40
	v_pk_fma_f32 v[102:103], s[40:41], v[168:169], v[102:103] op_sel_hi:[0,1,1]
	v_cvt_f32_ubyte3_e32 v171, v44
	v_cvt_f32_ubyte2_e32 v170, v44
	v_pk_fma_f32 v[102:103], s[38:39], v[170:171], v[102:103] op_sel_hi:[0,1,1]
	v_cvt_f32_ubyte3_e32 v169, v48
	v_cvt_f32_ubyte2_e32 v168, v48
	v_pk_fma_f32 v[102:103], s[42:43], v[168:169], v[102:103] op_sel_hi:[0,1,1]
	v_cvt_f32_ubyte3_e32 v171, v52
	v_cvt_f32_ubyte2_e32 v170, v52
	v_pk_fma_f32 v[102:103], s[2:3], v[170:171], v[102:103] op_sel_hi:[0,1,1]
	v_cvt_f32_ubyte1_e32 v169, v41
	v_cvt_f32_ubyte0_e32 v168, v41
	v_pk_fma_f32 v[98:99], s[40:41], v[168:169], v[98:99] op_sel_hi:[0,1,1]
	v_cvt_f32_ubyte1_e32 v171, v45
	v_cvt_f32_ubyte0_e32 v170, v45
	v_pk_fma_f32 v[98:99], s[38:39], v[170:171], v[98:99] op_sel_hi:[0,1,1]
	v_cvt_f32_ubyte1_e32 v169, v49
	v_cvt_f32_ubyte0_e32 v168, v49
	v_pk_fma_f32 v[98:99], s[42:43], v[168:169], v[98:99] op_sel_hi:[0,1,1]
	v_cvt_f32_ubyte1_e32 v171, v53
	v_cvt_f32_ubyte0_e32 v170, v53
	v_pk_fma_f32 v[98:99], s[2:3], v[170:171], v[98:99] op_sel_hi:[0,1,1]
	v_cvt_f32_ubyte3_e32 v169, v41
	v_cvt_f32_ubyte2_e32 v168, v41
	v_pk_fma_f32 v[100:101], s[40:41], v[168:169], v[100:101] op_sel_hi:[0,1,1]
	v_cvt_f32_ubyte3_e32 v171, v45
	v_cvt_f32_ubyte2_e32 v170, v45
	v_pk_fma_f32 v[100:101], s[38:39], v[170:171], v[100:101] op_sel_hi:[0,1,1]
	v_cvt_f32_ubyte3_e32 v169, v49
	v_cvt_f32_ubyte2_e32 v168, v49
	v_pk_fma_f32 v[100:101], s[42:43], v[168:169], v[100:101] op_sel_hi:[0,1,1]
	v_cvt_f32_ubyte3_e32 v171, v53
	v_cvt_f32_ubyte2_e32 v170, v53
	v_pk_fma_f32 v[100:101], s[2:3], v[170:171], v[100:101] op_sel_hi:[0,1,1]
	v_cvt_f32_ubyte1_e32 v169, v42
	v_cvt_f32_ubyte0_e32 v168, v42
	v_pk_fma_f32 v[94:95], s[40:41], v[168:169], v[94:95] op_sel_hi:[0,1,1]
	v_cvt_f32_ubyte1_e32 v171, v46
	v_cvt_f32_ubyte0_e32 v170, v46
	v_pk_fma_f32 v[94:95], s[38:39], v[170:171], v[94:95] op_sel_hi:[0,1,1]
	v_cvt_f32_ubyte1_e32 v169, v50
	v_cvt_f32_ubyte0_e32 v168, v50
	v_pk_fma_f32 v[94:95], s[42:43], v[168:169], v[94:95] op_sel_hi:[0,1,1]
	v_cvt_f32_ubyte1_e32 v171, v54
	v_cvt_f32_ubyte0_e32 v170, v54
	v_pk_fma_f32 v[94:95], s[2:3], v[170:171], v[94:95] op_sel_hi:[0,1,1]
	v_cvt_f32_ubyte3_e32 v169, v42
	v_cvt_f32_ubyte2_e32 v168, v42
	v_pk_fma_f32 v[96:97], s[40:41], v[168:169], v[96:97] op_sel_hi:[0,1,1]
	v_cvt_f32_ubyte3_e32 v171, v46
	v_cvt_f32_ubyte2_e32 v170, v46
	v_pk_fma_f32 v[96:97], s[38:39], v[170:171], v[96:97] op_sel_hi:[0,1,1]
	v_cvt_f32_ubyte3_e32 v169, v50
	v_cvt_f32_ubyte2_e32 v168, v50
	v_pk_fma_f32 v[96:97], s[42:43], v[168:169], v[96:97] op_sel_hi:[0,1,1]
	v_cvt_f32_ubyte3_e32 v171, v54
	v_cvt_f32_ubyte2_e32 v170, v54
	v_pk_fma_f32 v[96:97], s[2:3], v[170:171], v[96:97] op_sel_hi:[0,1,1]
	v_cvt_f32_ubyte1_e32 v169, v43
	v_cvt_f32_ubyte0_e32 v168, v43
	v_pk_fma_f32 v[90:91], s[40:41], v[168:169], v[90:91] op_sel_hi:[0,1,1]
	v_cvt_f32_ubyte1_e32 v171, v47
	v_cvt_f32_ubyte0_e32 v170, v47
	v_pk_fma_f32 v[90:91], s[38:39], v[170:171], v[90:91] op_sel_hi:[0,1,1]
	v_cvt_f32_ubyte1_e32 v169, v51
	v_cvt_f32_ubyte0_e32 v168, v51
	v_pk_fma_f32 v[90:91], s[42:43], v[168:169], v[90:91] op_sel_hi:[0,1,1]
	v_cvt_f32_ubyte1_e32 v171, v55
	v_cvt_f32_ubyte0_e32 v170, v55
	v_pk_fma_f32 v[90:91], s[2:3], v[170:171], v[90:91] op_sel_hi:[0,1,1]
	v_cvt_f32_ubyte3_e32 v169, v43
	v_cvt_f32_ubyte2_e32 v168, v43
	v_pk_fma_f32 v[92:93], s[40:41], v[168:169], v[92:93] op_sel_hi:[0,1,1]
	v_cvt_f32_ubyte3_e32 v171, v47
	v_cvt_f32_ubyte2_e32 v170, v47
	v_pk_fma_f32 v[92:93], s[38:39], v[170:171], v[92:93] op_sel_hi:[0,1,1]
	v_cvt_f32_ubyte3_e32 v169, v51
	v_cvt_f32_ubyte2_e32 v168, v51
	v_pk_fma_f32 v[92:93], s[42:43], v[168:169], v[92:93] op_sel_hi:[0,1,1]
	v_cvt_f32_ubyte3_e32 v171, v55
	v_cvt_f32_ubyte2_e32 v170, v55
	v_pk_fma_f32 v[92:93], s[2:3], v[170:171], v[92:93] op_sel_hi:[0,1,1]
	s_waitcnt vmcnt(10)
	s_cmp_eq_u32 s80, s33
	s_cbranch_scc1 .Lxp_noswa
	s_lshl_b32 s2, s33, 12
	v_add_u32_e32 v249, s2, v248
	ds_write_b128 v249, v[90:93]
	ds_write_b128 v249, v[94:97] offset:1024
	ds_write_b128 v249, v[98:101] offset:2048
	ds_write_b128 v249, v[102:105] offset:3072
	v_cmp_eq_u32_e32 vcc, s33, v60
	s_nop 1
	v_cndmask_b32_e32 v243, v243, v142, vcc
	s_lshl_b32 s2, s80, 12
	v_add_u32_e32 v249, s2, v248
	ds_read_b128 v[90:93], v249
	ds_read_b128 v[94:97], v249 offset:1024
	ds_read_b128 v[98:101], v249 offset:2048
	ds_read_b128 v[102:105], v249 offset:3072
	s_nop 0
	v_readlane_b32 s2, v243, s80
	v_readlane_b32 s3, v244, s80
	s_nop 1
	v_mov_b32_e32 v142, s2
	v_mov_b32_e32 v137, s3
	s_cmp_eq_u32 s80, 0
	s_cbranch_scc1 .Lxp_lxqa0
	s_cmp_eq_u32 s80, 1
	s_cbranch_scc1 .Lxp_lxqa1
	s_cmp_eq_u32 s80, 2
	s_cbranch_scc1 .Lxp_lxqa2
	v_mov_b32_e32 v133, v236
	v_mov_b32_e32 v134, v237
	v_mov_b32_e32 v135, v238
	v_mov_b32_e32 v136, v239
	s_branch .Lxp_lxqad

.Lxp_noswa:
	s_mov_b32 s80, s81
	s_mov_b32 s81, s94
	s_add_i32 s25, s25, 1
	s_cmp_eq_u32 s82, 1
	s_cbranch_scc0 .Lxp_folb
	s_lshl_b32 s2, s25, 7
	s_add_i32 s2, s2, s97
	s_and_b32 s2, s2, 0x3fff
	v_mov_b32_e32 v245, s2
	s_mov_b64 exec, 1
	global_store_dword v[246:247], v245, off
	s_mov_b64 exec, -1
	s_sleep 3
	s_waitcnt lgkmcnt(0)
	s_branch .Lxp_syncdb

.Lxp_syncdb:
	s_and_b32 s84, s84, 0x3fff
	s_lshl_b32 s2, s84, 11
	v_lshl_add_u32 v249, v60, 4, s2
	global_load_dwordx4 v[8:11], v249, s[18:19]
	global_load_dwordx4 v[40:43], v249, s[20:21]
	s_lshl_b32 s2, s84, 2
	v_writelane_b32 v147, s2, 0
	v_writelane_b32 v0, s85, 0
	s_and_b32 s86, s86, 0x3fff
	s_lshl_b32 s2, s86, 11
	v_lshl_add_u32 v249, v60, 4, s2
	global_load_dwordx4 v[16:19], v249, s[18:19]
	global_load_dwordx4 v[44:47], v249, s[20:21]
	s_lshl_b32 s2, s86, 2
	v_writelane_b32 v147, s2, 1
	v_writelane_b32 v0, s87, 1
	s_and_b32 s88, s88, 0x3fff
	s_lshl_b32 s2, s88, 11
	v_lshl_add_u32 v249, v60, 4, s2
	global_load_dwordx4 v[32:35], v249, s[18:19]
	global_load_dwordx4 v[48:51], v249, s[20:21]
	s_lshl_b32 s2, s88, 2
	v_writelane_b32 v147, s2, 2
	v_writelane_b32 v0, s89, 2
	s_and_b32 s90, s90, 0x3fff
	s_lshl_b32 s2, s90, 11
	v_lshl_add_u32 v249, v60, 4, s2
	global_load_dwordx4 v[36:39], v249, s[18:19]
	global_load_dwordx4 v[52:55], v249, s[20:21]
	s_lshl_b32 s2, s90, 2
	v_writelane_b32 v147, s2, 3
	v_writelane_b32 v0, s91, 3
	global_load_dword v138, v147, s[44:45]
	global_load_dword v139, v147, s[46:47]
	s_add_i32 s3, s25, 3
	s_min_u32 s3, s3, 0x7f
	s_cmp_lt_u32 s3, 64
	s_cselect_b64 vcc, -1, 0
	s_nop 0
	v_cndmask_b32_e32 v249, v241, v240, vcc
	s_nop 1
	v_readlane_b32 s2, v249, s3
	s_and_b32 s3, s2, 31
	s_lshl_b32 s3, s3, 5
	s_bfe_u32 s94, s2, 0x20005
	s_lshl_b32 s2, s94, 11
	s_add_i32 s3, s3, s2
	s_load_dwordx8 s[84:91], s[36:37], s3
	v_mov_b32_e32 v149, 0
	v_mov_b32_e32 v150, 0
	v_mov_b32_e32 v151, 0
	v_mov_b32_e32 v148, 0
	v_dot4c_i32_i8_e32 v149, v152, v133
	v_dot4c_i32_i8_e32 v150, v156, v133
	v_dot4c_i32_i8_e32 v151, v160, v133
	v_dot4c_i32_i8_e32 v148, v164, v133
	v_dot4c_i32_i8_e32 v149, v153, v134
	v_dot4c_i32_i8_e32 v150, v157, v134
	v_dot4c_i32_i8_e32 v151, v161, v134
	v_dot4c_i32_i8_e32 v148, v165, v134
	v_dot4c_i32_i8_e32 v149, v154, v135
	v_dot4c_i32_i8_e32 v150, v158, v135
	v_dot4c_i32_i8_e32 v151, v162, v135
	v_dot4c_i32_i8_e32 v148, v166, v135
	v_dot4c_i32_i8_e32 v149, v155, v136
	v_dot4c_i32_i8_e32 v150, v159, v136
	v_dot4c_i32_i8_e32 v151, v163, v136
	v_dot4c_i32_i8_e32 v148, v167, v136
	s_nop 3
	v_cndmask_b32_e64 v143, v149, v150, s[0:1]
	v_cndmask_b32_e64 v144, v150, v149, s[0:1]
	v_cndmask_b32_e64 v145, v151, v148, s[0:1]
	v_cndmask_b32_e64 v146, v148, v151, s[0:1]
	s_nop 1
	v_add_u32_dpp v144, v143, v144 quad_perm:[1,0,3,2] row_mask:0xf bank_mask:0xf
	v_add_u32_dpp v146, v145, v146 quad_perm:[1,0,3,2] row_mask:0xf bank_mask:0xf
	s_nop 1
	v_cndmask_b32_e64 v143, v144, v146, s[6:7]
	v_cndmask_b32_e64 v145, v146, v144, s[6:7]
	s_nop 1
	v_add_u32_dpp v145, v143, v145 quad_perm:[2,3,0,1] row_mask:0xf bank_mask:0xf
	s_nop 1
	v_add_u32_dpp v145, v145, v145 row_ror:4 row_mask:0xf bank_mask:0xf
	s_nop 1
	v_add_u32_dpp v145, v145, v145 row_ror:8 row_mask:0xf bank_mask:0xf
	s_nop 1
	ds_bpermute_b32 v143, v126, v145
	s_waitcnt lgkmcnt(0)
	v_add_u32_e32 v145, v145, v143
	ds_bpermute_b32 v143, v127, v145
	s_waitcnt lgkmcnt(0)
	v_add_u32_e32 v145, v145, v143
	v_cvt_f32_i32_e32 v56, v145
	v_mul_f32_e32 v59, v140, v56
	v_mul_f32_e32 v59, v137, v59
	v_mul_f32_e32 v56, 0x3f3504f3, v59
	v_fma_f32 v143, |v56|, s66, v120
	v_fma_f32 v143, |v56|, v143, s67
	v_fma_f32 v143, |v56|, v143, s68
	v_fma_f32 v143, |v56|, v143, s69
	v_fma_f32 v143, |v56|, v143, s70
	v_fma_f32 v143, |v56|, v143, s71
	v_fma_f32 v143, |v56|, v143, |v56|
	v_mul_f32_e32 v144, 0xbfb8aa3b, v143
	v_fma_f32 v146, v143, s72, -v144
	v_rndne_f32_e32 v3, v144
	v_fmac_f32_e32 v146, 0xb2a5705f, v143
	v_sub_f32_e32 v144, v144, v3
	v_add_f32_e32 v144, v144, v146
	v_cvt_i32_f32_e32 v146, v3
	v_exp_f32_e32 v144, v144
	v_cmp_nlt_f32_e32 vcc, s73, v143
	v_ldexp_f32 v144, v144, v146
	s_nop 0
	v_cndmask_b32_e32 v144, 0, v144, vcc
	v_cmp_ngt_f32_e32 vcc, s74, v143
	s_nop 1
	v_cndmask_b32_e32 v143, v121, v144, vcc
	v_sub_f32_e32 v143, 1.0, v143
	v_mul_f32_e32 v168, v56, v56
	v_fmamk_f32 v169, v168, 0xba1345e1, v117
	v_fmaak_f32 v169, v168, v169, 0xbcdac9b8
	v_fmaak_f32 v169, v168, v169, 0x3de703be
	v_fmaak_f32 v169, v168, v169, 0xbec09330
	v_fmaak_f32 v168, v168, v169, 0x3e0375d0
	v_fma_f32 v168, |v56|, v168, |v56|
	v_cmp_nlt_f32_e64 vcc, |v56|, 1.0
	s_nop 1
	v_cndmask_b32_e32 v143, v168, v143, vcc
	v_bfi_b32 v146, s75, v143, v56
	v_mul_f32_e32 v145, 0.5, v59
	v_add_f32_e32 v146, 1.0, v146
	v_mul_f32_e32 v145, v145, v146
	v_mul_f32_e32 v144, v1, v145
	v_mul_f32_e32 v143, v141, v144
	s_nop 1
	v_readlane_b32 s40, v143, 0
	v_readlane_b32 s38, v143, 1
	v_readlane_b32 s42, v143, 2
	v_readlane_b32 s2, v143, 3
	s_nop 1
	v_add_f32_e32 v142, s40, v142
	v_add_f32_e32 v142, s38, v142
	v_add_f32_e32 v142, s42, v142
	v_add_f32_e32 v142, s2, v142
	v_cvt_f32_ubyte1_e32 v169, v12
	v_cvt_f32_ubyte0_e32 v168, v12
	v_pk_fma_f32 v[104:105], s[40:41], v[168:169], v[104:105] op_sel_hi:[0,1,1]
	v_cvt_f32_ubyte1_e32 v171, v20
	v_cvt_f32_ubyte0_e32 v170, v20
	v_pk_fma_f32 v[104:105], s[38:39], v[170:171], v[104:105] op_sel_hi:[0,1,1]
	v_cvt_f32_ubyte1_e32 v169, v24
	v_cvt_f32_ubyte0_e32 v168, v24
	v_pk_fma_f32 v[104:105], s[42:43], v[168:169], v[104:105] op_sel_hi:[0,1,1]
	v_cvt_f32_ubyte1_e32 v171, v28
	v_cvt_f32_ubyte0_e32 v170, v28
	v_pk_fma_f32 v[104:105], s[2:3], v[170:171], v[104:105] op_sel_hi:[0,1,1]
	v_cvt_f32_ubyte3_e32 v169, v12
	v_cvt_f32_ubyte2_e32 v168, v12
	v_pk_fma_f32 v[102:103], s[40:41], v[168:169], v[102:103] op_sel_hi:[0,1,1]
	v_cvt_f32_ubyte3_e32 v171, v20
	v_cvt_f32_ubyte2_e32 v170, v20
	v_pk_fma_f32 v[102:103], s[38:39], v[170:171], v[102:103] op_sel_hi:[0,1,1]
	v_cvt_f32_ubyte3_e32 v169, v24
	v_cvt_f32_ubyte2_e32 v168, v24
	v_pk_fma_f32 v[102:103], s[42:43], v[168:169], v[102:103] op_sel_hi:[0,1,1]
	v_cvt_f32_ubyte3_e32 v171, v28
	v_cvt_f32_ubyte2_e32 v170, v28
	v_pk_fma_f32 v[102:103], s[2:3], v[170:171], v[102:103] op_sel_hi:[0,1,1]
	v_cvt_f32_ubyte1_e32 v169, v13
	v_cvt_f32_ubyte0_e32 v168, v13
	v_pk_fma_f32 v[98:99], s[40:41], v[168:169], v[98:99] op_sel_hi:[0,1,1]
	v_cvt_f32_ubyte1_e32 v171, v21
	v_cvt_f32_ubyte0_e32 v170, v21
	v_pk_fma_f32 v[98:99], s[38:39], v[170:171], v[98:99] op_sel_hi:[0,1,1]
	v_cvt_f32_ubyte1_e32 v169, v25
	v_cvt_f32_ubyte0_e32 v168, v25
	v_pk_fma_f32 v[98:99], s[42:43], v[168:169], v[98:99] op_sel_hi:[0,1,1]
	v_cvt_f32_ubyte1_e32 v171, v29
	v_cvt_f32_ubyte0_e32 v170, v29
	v_pk_fma_f32 v[98:99], s[2:3], v[170:171], v[98:99] op_sel_hi:[0,1,1]
	v_cvt_f32_ubyte3_e32 v169, v13
	v_cvt_f32_ubyte2_e32 v168, v13
	v_pk_fma_f32 v[100:101], s[40:41], v[168:169], v[100:101] op_sel_hi:[0,1,1]
	v_cvt_f32_ubyte3_e32 v171, v21
	v_cvt_f32_ubyte2_e32 v170, v21
	v_pk_fma_f32 v[100:101], s[38:39], v[170:171], v[100:101] op_sel_hi:[0,1,1]
	v_cvt_f32_ubyte3_e32 v169, v25
	v_cvt_f32_ubyte2_e32 v168, v25
	v_pk_fma_f32 v[100:101], s[42:43], v[168:169], v[100:101] op_sel_hi:[0,1,1]
	v_cvt_f32_ubyte3_e32 v171, v29
	v_cvt_f32_ubyte2_e32 v170, v29
	v_pk_fma_f32 v[100:101], s[2:3], v[170:171], v[100:101] op_sel_hi:[0,1,1]
	v_cvt_f32_ubyte1_e32 v169, v14
	v_cvt_f32_ubyte0_e32 v168, v14
	v_pk_fma_f32 v[94:95], s[40:41], v[168:169], v[94:95] op_sel_hi:[0,1,1]
	v_cvt_f32_ubyte1_e32 v171, v22
	v_cvt_f32_ubyte0_e32 v170, v22
	v_pk_fma_f32 v[94:95], s[38:39], v[170:171], v[94:95] op_sel_hi:[0,1,1]
	v_cvt_f32_ubyte1_e32 v169, v26
	v_cvt_f32_ubyte0_e32 v168, v26
	v_pk_fma_f32 v[94:95], s[42:43], v[168:169], v[94:95] op_sel_hi:[0,1,1]
	v_cvt_f32_ubyte1_e32 v171, v30
	v_cvt_f32_ubyte0_e32 v170, v30
	v_pk_fma_f32 v[94:95], s[2:3], v[170:171], v[94:95] op_sel_hi:[0,1,1]
	v_cvt_f32_ubyte3_e32 v169, v14
	v_cvt_f32_ubyte2_e32 v168, v14
	v_pk_fma_f32 v[96:97], s[40:41], v[168:169], v[96:97] op_sel_hi:[0,1,1]
	v_cvt_f32_ubyte3_e32 v171, v22
	v_cvt_f32_ubyte2_e32 v170, v22
	v_pk_fma_f32 v[96:97], s[38:39], v[170:171], v[96:97] op_sel_hi:[0,1,1]
	v_cvt_f32_ubyte3_e32 v169, v26
	v_cvt_f32_ubyte2_e32 v168, v26
	v_pk_fma_f32 v[96:97], s[42:43], v[168:169], v[96:97] op_sel_hi:[0,1,1]
	v_cvt_f32_ubyte3_e32 v171, v30
	v_cvt_f32_ubyte2_e32 v170, v30
	v_pk_fma_f32 v[96:97], s[2:3], v[170:171], v[96:97] op_sel_hi:[0,1,1]
	v_cvt_f32_ubyte1_e32 v169, v15
	v_cvt_f32_ubyte0_e32 v168, v15
	v_pk_fma_f32 v[90:91], s[40:41], v[168:169], v[90:91] op_sel_hi:[0,1,1]
	v_cvt_f32_ubyte1_e32 v171, v23
	v_cvt_f32_ubyte0_e32 v170, v23
	v_pk_fma_f32 v[90:91], s[38:39], v[170:171], v[90:91] op_sel_hi:[0,1,1]
	v_cvt_f32_ubyte1_e32 v169, v27
	v_cvt_f32_ubyte0_e32 v168, v27
	v_pk_fma_f32 v[90:91], s[42:43], v[168:169], v[90:91] op_sel_hi:[0,1,1]
	v_cvt_f32_ubyte1_e32 v171, v31
	v_cvt_f32_ubyte0_e32 v170, v31
	v_pk_fma_f32 v[90:91], s[2:3], v[170:171], v[90:91] op_sel_hi:[0,1,1]
	v_cvt_f32_ubyte3_e32 v169, v15
	v_cvt_f32_ubyte2_e32 v168, v15
	v_pk_fma_f32 v[92:93], s[40:41], v[168:169], v[92:93] op_sel_hi:[0,1,1]
	v_cvt_f32_ubyte3_e32 v171, v23
	v_cvt_f32_ubyte2_e32 v170, v23
	v_pk_fma_f32 v[92:93], s[38:39], v[170:171], v[92:93] op_sel_hi:[0,1,1]
	v_cvt_f32_ubyte3_e32 v169, v27
	v_cvt_f32_ubyte2_e32 v168, v27
	v_pk_fma_f32 v[92:93], s[42:43], v[168:169], v[92:93] op_sel_hi:[0,1,1]
	v_cvt_f32_ubyte3_e32 v171, v31
	v_cvt_f32_ubyte2_e32 v170, v31
	v_pk_fma_f32 v[92:93], s[2:3], v[170:171], v[92:93] op_sel_hi:[0,1,1]
	s_waitcnt vmcnt(10)
	s_cmp_eq_u32 s80, s33
	s_cbranch_scc1 .Lxp_noswb
	s_lshl_b32 s2, s33, 12
	v_add_u32_e32 v249, s2, v248
	ds_write_b128 v249, v[90:93]
	ds_write_b128 v249, v[94:97] offset:1024
	ds_write_b128 v249, v[98:101] offset:2048
	ds_write_b128 v249, v[102:105] offset:3072
	v_cmp_eq_u32_e32 vcc, s33, v60
	s_nop 1
	v_cndmask_b32_e32 v243, v243, v142, vcc
	s_lshl_b32 s2, s80, 12
	v_add_u32_e32 v249, s2, v248
	ds_read_b128 v[90:93], v249
	ds_read_b128 v[94:97], v249 offset:1024
	ds_read_b128 v[98:101], v249 offset:2048
	ds_read_b128 v[102:105], v249 offset:3072
	s_nop 0
	v_readlane_b32 s2, v243, s80
	v_readlane_b32 s3, v244, s80
	s_nop 1
	v_mov_b32_e32 v142, s2
	v_mov_b32_e32 v137, s3
	s_cmp_eq_u32 s80, 0
	s_cbranch_scc1 .Lxp_lxqb0
	s_cmp_eq_u32 s80, 1
	s_cbranch_scc1 .Lxp_lxqb1
	s_cmp_eq_u32 s80, 2
	s_cbranch_scc1 .Lxp_lxqb2
	v_mov_b32_e32 v133, v236
	v_mov_b32_e32 v134, v237
	v_mov_b32_e32 v135, v238
	v_mov_b32_e32 v136, v239
	s_branch .Lxp_lxqbd

.Lxp_syncdc:
	s_and_b32 s84, s84, 0x3fff
	s_lshl_b32 s2, s84, 11
	v_lshl_add_u32 v249, v60, 4, s2
	global_load_dwordx4 v[152:155], v249, s[18:19]
	global_load_dwordx4 v[12:15], v249, s[20:21]
	s_lshl_b32 s2, s84, 2
	v_writelane_b32 v147, s2, 0
	v_writelane_b32 v1, s85, 0
	s_and_b32 s86, s86, 0x3fff
	s_lshl_b32 s2, s86, 11
	v_lshl_add_u32 v249, v60, 4, s2
	global_load_dwordx4 v[156:159], v249, s[18:19]
	global_load_dwordx4 v[20:23], v249, s[20:21]
	s_lshl_b32 s2, s86, 2
	v_writelane_b32 v147, s2, 1
	v_writelane_b32 v1, s87, 1
	s_and_b32 s88, s88, 0x3fff
	s_lshl_b32 s2, s88, 11
	v_lshl_add_u32 v249, v60, 4, s2
	global_load_dwordx4 v[160:163], v249, s[18:19]
	global_load_dwordx4 v[24:27], v249, s[20:21]
	s_lshl_b32 s2, s88, 2
	v_writelane_b32 v147, s2, 2
	v_writelane_b32 v1, s89, 2
	s_and_b32 s90, s90, 0x3fff
	s_lshl_b32 s2, s90, 11
	v_lshl_add_u32 v249, v60, 4, s2
	global_load_dwordx4 v[164:167], v249, s[18:19]
	global_load_dwordx4 v[28:31], v249, s[20:21]
	s_lshl_b32 s2, s90, 2
	v_writelane_b32 v147, s2, 3
	v_writelane_b32 v1, s91, 3
	global_load_dword v140, v147, s[44:45]
	global_load_dword v141, v147, s[46:47]
	s_add_i32 s3, s25, 3
	s_min_u32 s3, s3, 0x7f
	s_cmp_lt_u32 s3, 64
	s_cselect_b64 vcc, -1, 0
	s_nop 0
	v_cndmask_b32_e32 v249, v241, v240, vcc
	s_nop 1
	v_readlane_b32 s2, v249, s3
	s_and_b32 s3, s2, 31
	s_lshl_b32 s3, s3, 5
	s_bfe_u32 s94, s2, 0x20005
	s_lshl_b32 s2, s94, 11
	s_add_i32 s3, s3, s2
	s_load_dwordx8 s[84:91], s[36:37], s3
	v_mov_b32_e32 v149, 0
	v_mov_b32_e32 v150, 0
	v_mov_b32_e32 v151, 0
	v_mov_b32_e32 v148, 0
	v_dot4c_i32_i8_e32 v149, v72, v133
	v_dot4c_i32_i8_e32 v150, v76, v133
	v_dot4c_i32_i8_e32 v151, v80, v133
	v_dot4c_i32_i8_e32 v148, v84, v133
	v_dot4c_i32_i8_e32 v149, v73, v134
	v_dot4c_i32_i8_e32 v150, v77, v134
	v_dot4c_i32_i8_e32 v151, v81, v134
	v_dot4c_i32_i8_e32 v148, v85, v134
	v_dot4c_i32_i8_e32 v149, v74, v135
	v_dot4c_i32_i8_e32 v150, v78, v135
	v_dot4c_i32_i8_e32 v151, v82, v135
	v_dot4c_i32_i8_e32 v148, v86, v135
	v_dot4c_i32_i8_e32 v149, v75, v136
	v_dot4c_i32_i8_e32 v150, v79, v136
	v_dot4c_i32_i8_e32 v151, v83, v136
	v_dot4c_i32_i8_e32 v148, v87, v136
	s_nop 3
	v_cndmask_b32_e64 v143, v149, v150, s[0:1]
	v_cndmask_b32_e64 v144, v150, v149, s[0:1]
	v_cndmask_b32_e64 v145, v151, v148, s[0:1]
	v_cndmask_b32_e64 v146, v148, v151, s[0:1]
	s_nop 1
	v_add_u32_dpp v144, v143, v144 quad_perm:[1,0,3,2] row_mask:0xf bank_mask:0xf
	v_add_u32_dpp v146, v145, v146 quad_perm:[1,0,3,2] row_mask:0xf bank_mask:0xf
	s_nop 1
	v_cndmask_b32_e64 v143, v144, v146, s[6:7]
	v_cndmask_b32_e64 v145, v146, v144, s[6:7]
	s_nop 1
	v_add_u32_dpp v145, v143, v145 quad_perm:[2,3,0,1] row_mask:0xf bank_mask:0xf
	s_nop 1
	v_add_u32_dpp v145, v145, v145 row_ror:4 row_mask:0xf bank_mask:0xf
	s_nop 1
	v_add_u32_dpp v145, v145, v145 row_ror:8 row_mask:0xf bank_mask:0xf
	s_nop 1
	ds_bpermute_b32 v143, v126, v145
	s_waitcnt lgkmcnt(0)
	v_add_u32_e32 v145, v145, v143
	ds_bpermute_b32 v143, v127, v145
	s_waitcnt lgkmcnt(0)
	v_add_u32_e32 v145, v145, v143
	v_cvt_f32_i32_e32 v56, v145
	v_mul_f32_e32 v59, v88, v56
	v_mul_f32_e32 v59, v137, v59
	v_mul_f32_e32 v56, 0x3f3504f3, v59
	v_fma_f32 v143, |v56|, s66, v120
	v_fma_f32 v143, |v56|, v143, s67
	v_fma_f32 v143, |v56|, v143, s68
	v_fma_f32 v143, |v56|, v143, s69
	v_fma_f32 v143, |v56|, v143, s70
	v_fma_f32 v143, |v56|, v143, s71
	v_fma_f32 v143, |v56|, v143, |v56|
	v_mul_f32_e32 v144, 0xbfb8aa3b, v143
	v_fma_f32 v146, v143, s72, -v144
	v_rndne_f32_e32 v3, v144
	v_fmac_f32_e32 v146, 0xb2a5705f, v143
	v_sub_f32_e32 v144, v144, v3
	v_add_f32_e32 v144, v144, v146
	v_cvt_i32_f32_e32 v146, v3
	v_exp_f32_e32 v144, v144
	v_cmp_nlt_f32_e32 vcc, s73, v143
	v_ldexp_f32 v144, v144, v146
	s_nop 0
	v_cndmask_b32_e32 v144, 0, v144, vcc
	v_cmp_ngt_f32_e32 vcc, s74, v143
	s_nop 1
	v_cndmask_b32_e32 v143, v121, v144, vcc
	v_sub_f32_e32 v143, 1.0, v143
	v_mul_f32_e32 v168, v56, v56
	v_fmamk_f32 v169, v168, 0xba1345e1, v117
	v_fmaak_f32 v169, v168, v169, 0xbcdac9b8
	v_fmaak_f32 v169, v168, v169, 0x3de703be
	v_fmaak_f32 v169, v168, v169, 0xbec09330
	v_fmaak_f32 v168, v168, v169, 0x3e0375d0
	v_fma_f32 v168, |v56|, v168, |v56|
	v_cmp_nlt_f32_e64 vcc, |v56|, 1.0
	s_nop 1
	v_cndmask_b32_e32 v143, v168, v143, vcc
	v_bfi_b32 v146, s75, v143, v56
	v_mul_f32_e32 v145, 0.5, v59
	v_add_f32_e32 v146, 1.0, v146
	v_mul_f32_e32 v145, v145, v146
	v_mul_f32_e32 v144, v2, v145
	v_mul_f32_e32 v143, v89, v144
	s_nop 1
	v_readlane_b32 s40, v143, 0
	v_readlane_b32 s38, v143, 1
	v_readlane_b32 s42, v143, 2
	v_readlane_b32 s2, v143, 3
	s_nop 1
	v_add_f32_e32 v142, s40, v142
	v_add_f32_e32 v142, s38, v142
	v_add_f32_e32 v142, s42, v142
	v_add_f32_e32 v142, s2, v142
	v_cvt_f32_ubyte1_e32 v169, v64
	v_cvt_f32_ubyte0_e32 v168, v64
	v_pk_fma_f32 v[104:105], s[40:41], v[168:169], v[104:105] op_sel_hi:[0,1,1]
	v_cvt_f32_ubyte1_e32 v171, v68
	v_cvt_f32_ubyte0_e32 v170, v68
	v_pk_fma_f32 v[104:105], s[38:39], v[170:171], v[104:105] op_sel_hi:[0,1,1]
	v_cvt_f32_ubyte1_e32 v169, v4
	v_cvt_f32_ubyte0_e32 v168, v4
	v_pk_fma_f32 v[104:105], s[42:43], v[168:169], v[104:105] op_sel_hi:[0,1,1]
	v_cvt_f32_ubyte1_e32 v171, v128
	v_cvt_f32_ubyte0_e32 v170, v128
	v_pk_fma_f32 v[104:105], s[2:3], v[170:171], v[104:105] op_sel_hi:[0,1,1]
	v_cvt_f32_ubyte3_e32 v169, v64
	v_cvt_f32_ubyte2_e32 v168, v64
	v_pk_fma_f32 v[102:103], s[40:41], v[168:169], v[102:103] op_sel_hi:[0,1,1]
	v_cvt_f32_ubyte3_e32 v171, v68
	v_cvt_f32_ubyte2_e32 v170, v68
	v_pk_fma_f32 v[102:103], s[38:39], v[170:171], v[102:103] op_sel_hi:[0,1,1]
	v_cvt_f32_ubyte3_e32 v169, v4
	v_cvt_f32_ubyte2_e32 v168, v4
	v_pk_fma_f32 v[102:103], s[42:43], v[168:169], v[102:103] op_sel_hi:[0,1,1]
	v_cvt_f32_ubyte3_e32 v171, v128
	v_cvt_f32_ubyte2_e32 v170, v128
	v_pk_fma_f32 v[102:103], s[2:3], v[170:171], v[102:103] op_sel_hi:[0,1,1]
	v_cvt_f32_ubyte1_e32 v169, v65
	v_cvt_f32_ubyte0_e32 v168, v65
	v_pk_fma_f32 v[98:99], s[40:41], v[168:169], v[98:99] op_sel_hi:[0,1,1]
	v_cvt_f32_ubyte1_e32 v171, v69
	v_cvt_f32_ubyte0_e32 v170, v69
	v_pk_fma_f32 v[98:99], s[38:39], v[170:171], v[98:99] op_sel_hi:[0,1,1]
	v_cvt_f32_ubyte1_e32 v169, v5
	v_cvt_f32_ubyte0_e32 v168, v5
	v_pk_fma_f32 v[98:99], s[42:43], v[168:169], v[98:99] op_sel_hi:[0,1,1]
	v_cvt_f32_ubyte1_e32 v171, v129
	v_cvt_f32_ubyte0_e32 v170, v129
	v_pk_fma_f32 v[98:99], s[2:3], v[170:171], v[98:99] op_sel_hi:[0,1,1]
	v_cvt_f32_ubyte3_e32 v169, v65
	v_cvt_f32_ubyte2_e32 v168, v65
	v_pk_fma_f32 v[100:101], s[40:41], v[168:169], v[100:101] op_sel_hi:[0,1,1]
	v_cvt_f32_ubyte3_e32 v171, v69
	v_cvt_f32_ubyte2_e32 v170, v69
	v_pk_fma_f32 v[100:101], s[38:39], v[170:171], v[100:101] op_sel_hi:[0,1,1]
	v_cvt_f32_ubyte3_e32 v169, v5
	v_cvt_f32_ubyte2_e32 v168, v5
	v_pk_fma_f32 v[100:101], s[42:43], v[168:169], v[100:101] op_sel_hi:[0,1,1]
	v_cvt_f32_ubyte3_e32 v171, v129
	v_cvt_f32_ubyte2_e32 v170, v129
	v_pk_fma_f32 v[100:101], s[2:3], v[170:171], v[100:101] op_sel_hi:[0,1,1]
	v_cvt_f32_ubyte1_e32 v169, v66
	v_cvt_f32_ubyte0_e32 v168, v66
	v_pk_fma_f32 v[94:95], s[40:41], v[168:169], v[94:95] op_sel_hi:[0,1,1]
	v_cvt_f32_ubyte1_e32 v171, v70
	v_cvt_f32_ubyte0_e32 v170, v70
	v_pk_fma_f32 v[94:95], s[38:39], v[170:171], v[94:95] op_sel_hi:[0,1,1]
	v_cvt_f32_ubyte1_e32 v169, v6
	v_cvt_f32_ubyte0_e32 v168, v6
	v_pk_fma_f32 v[94:95], s[42:43], v[168:169], v[94:95] op_sel_hi:[0,1,1]
	v_cvt_f32_ubyte1_e32 v171, v130
	v_cvt_f32_ubyte0_e32 v170, v130
	v_pk_fma_f32 v[94:95], s[2:3], v[170:171], v[94:95] op_sel_hi:[0,1,1]
	v_cvt_f32_ubyte3_e32 v169, v66
	v_cvt_f32_ubyte2_e32 v168, v66
	v_pk_fma_f32 v[96:97], s[40:41], v[168:169], v[96:97] op_sel_hi:[0,1,1]
	v_cvt_f32_ubyte3_e32 v171, v70
	v_cvt_f32_ubyte2_e32 v170, v70
	v_pk_fma_f32 v[96:97], s[38:39], v[170:171], v[96:97] op_sel_hi:[0,1,1]
	v_cvt_f32_ubyte3_e32 v169, v6
	v_cvt_f32_ubyte2_e32 v168, v6
	v_pk_fma_f32 v[96:97], s[42:43], v[168:169], v[96:97] op_sel_hi:[0,1,1]
	v_cvt_f32_ubyte3_e32 v171, v130
	v_cvt_f32_ubyte2_e32 v170, v130
	v_pk_fma_f32 v[96:97], s[2:3], v[170:171], v[96:97] op_sel_hi:[0,1,1]
	v_cvt_f32_ubyte1_e32 v169, v67
	v_cvt_f32_ubyte0_e32 v168, v67
	v_pk_fma_f32 v[90:91], s[40:41], v[168:169], v[90:91] op_sel_hi:[0,1,1]
	v_cvt_f32_ubyte1_e32 v171, v71
	v_cvt_f32_ubyte0_e32 v170, v71
	v_pk_fma_f32 v[90:91], s[38:39], v[170:171], v[90:91] op_sel_hi:[0,1,1]
	v_cvt_f32_ubyte1_e32 v169, v7
	v_cvt_f32_ubyte0_e32 v168, v7
	v_pk_fma_f32 v[90:91], s[42:43], v[168:169], v[90:91] op_sel_hi:[0,1,1]
	v_cvt_f32_ubyte1_e32 v171, v131
	v_cvt_f32_ubyte0_e32 v170, v131
	v_pk_fma_f32 v[90:91], s[2:3], v[170:171], v[90:91] op_sel_hi:[0,1,1]
	v_cvt_f32_ubyte3_e32 v169, v67
	v_cvt_f32_ubyte2_e32 v168, v67
	v_pk_fma_f32 v[92:93], s[40:41], v[168:169], v[92:93] op_sel_hi:[0,1,1]
	v_cvt_f32_ubyte3_e32 v171, v71
	v_cvt_f32_ubyte2_e32 v170, v71
	v_pk_fma_f32 v[92:93], s[38:39], v[170:171], v[92:93] op_sel_hi:[0,1,1]
	v_cvt_f32_ubyte3_e32 v169, v7
	v_cvt_f32_ubyte2_e32 v168, v7
	v_pk_fma_f32 v[92:93], s[42:43], v[168:169], v[92:93] op_sel_hi:[0,1,1]
	v_cvt_f32_ubyte3_e32 v171, v131
	v_cvt_f32_ubyte2_e32 v170, v131
	v_pk_fma_f32 v[92:93], s[2:3], v[170:171], v[92:93] op_sel_hi:[0,1,1]
	s_waitcnt vmcnt(10)
	s_cmp_eq_u32 s80, s33
	s_cbranch_scc1 .Lxp_noswc
	s_lshl_b32 s2, s33, 12
	v_add_u32_e32 v249, s2, v248
	ds_write_b128 v249, v[90:93]
	ds_write_b128 v249, v[94:97] offset:1024
	ds_write_b128 v249, v[98:101] offset:2048
	ds_write_b128 v249, v[102:105] offset:3072
	v_cmp_eq_u32_e32 vcc, s33, v60
	s_nop 1
	v_cndmask_b32_e32 v243, v243, v142, vcc
	s_lshl_b32 s2, s80, 12
	v_add_u32_e32 v249, s2, v248
	ds_read_b128 v[90:93], v249
	ds_read_b128 v[94:97], v249 offset:1024
	ds_read_b128 v[98:101], v249 offset:2048
	ds_read_b128 v[102:105], v249 offset:3072
	s_nop 0
	v_readlane_b32 s2, v243, s80
	v_readlane_b32 s3, v244, s80
	s_nop 1
	v_mov_b32_e32 v142, s2
	v_mov_b32_e32 v137, s3
	s_cmp_eq_u32 s80, 0
	s_cbranch_scc1 .Lxp_lxqc0
	s_cmp_eq_u32 s80, 1
	s_cbranch_scc1 .Lxp_lxqc1
	s_cmp_eq_u32 s80, 2
	s_cbranch_scc1 .Lxp_lxqc2
	v_mov_b32_e32 v133, v236
	v_mov_b32_e32 v134, v237
	v_mov_b32_e32 v135, v238
	v_mov_b32_e32 v136, v239
	s_branch .Lxp_lxqcd

.Lxp_noswc:
	s_mov_b32 s80, s81
	s_mov_b32 s81, s94
	s_add_i32 s25, s25, 1
	s_cmp_lt_u32 s25, 126
	s_cbranch_scc1 .Lxp_unit
	s_cmp_eq_u32 s82, 1
	s_cbranch_scc0 .Lxp_fold
	s_lshl_b32 s2, s25, 7
	s_add_i32 s2, s2, s97
	s_and_b32 s2, s2, 0x3fff
	v_mov_b32_e32 v245, s2
	s_mov_b64 exec, 1
	global_store_dword v[246:247], v245, off
	s_mov_b64 exec, -1
	s_sleep 3
	s_waitcnt lgkmcnt(0)
	s_branch .Lxp_syncdd

.Lxp_noswe:
	s_mov_b32 s80, s81
	s_mov_b32 s81, s94
	s_add_i32 s25, s25, 1
	s_waitcnt vmcnt(0) lgkmcnt(0)
	s_lshl_b32 s2, s33, 12
	v_add_u32_e32 v249, s2, v248
	ds_write_b128 v249, v[90:93]
	ds_write_b128 v249, v[94:97] offset:1024
	ds_write_b128 v249, v[98:101] offset:2048
	ds_write_b128 v249, v[102:105] offset:3072
	v_cmp_eq_u32_e32 vcc, s33, v60
	s_nop 1
	v_cndmask_b32_e32 v243, v243, v142, vcc
	v_readlane_b32 s76, v254, 34
	v_readlane_b32 s77, v254, 35
	s_mov_b32 s25, 0
.Lxp_out:
	s_lshl_b32 s2, s25, 12
	v_add_u32_e32 v249, s2, v248
	ds_read_b128 v[90:93], v249
	ds_read_b128 v[94:97], v249 offset:1024
	ds_read_b128 v[98:101], v249 offset:2048
	ds_read_b128 v[102:105], v249 offset:3072
	s_add_i32 s2, s32, s25
	s_lshl_b32 s3, s2, 11
	v_lshl_add_u32 v250, v60, 5, s3
	global_load_dwordx4 v[0:3], v250, s[16:17] offset:16
	global_load_dwordx4 v[4:7], v250, s[16:17]
	s_lshl_b32 s2, s2, 12
	v_lshl_add_u32 v251, v60, 6, s2
	v_readlane_b32 s3, v243, s25
	s_waitcnt vmcnt(0) lgkmcnt(0)
	v_mov_b32_e32 v142, s3
	v_lshlrev_b32_e32 v84, 16, v4
	v_and_b32_e32 v85, 0xffff0000, v4
	v_lshlrev_b32_e32 v86, 16, v5
	v_and_b32_e32 v87, 0xffff0000, v5
	v_lshlrev_b32_e32 v80, 16, v6
	v_and_b32_e32 v81, 0xffff0000, v6
	v_lshlrev_b32_e32 v82, 16, v7
	v_and_b32_e32 v83, 0xffff0000, v7
	v_lshlrev_b32_e32 v76, 16, v0
	v_and_b32_e32 v77, 0xffff0000, v0
	v_lshlrev_b32_e32 v78, 16, v1
	v_and_b32_e32 v79, 0xffff0000, v1
	v_lshlrev_b32_e32 v72, 16, v2
	v_and_b32_e32 v73, 0xffff0000, v2
	v_lshlrev_b32_e32 v74, 16, v3
	v_and_b32_e32 v75, 0xffff0000, v3
	v_pk_add_f32 v[8:9], v[104:105], v[84:85]
	v_pk_add_f32 v[10:11], v[102:103], v[86:87]
	v_fmac_f32_e32 v8, 0xc3000000, v142
	v_fmac_f32_e32 v9, 0xc3000000, v142
	v_fmac_f32_e32 v10, 0xc3000000, v142
	v_fmac_f32_e32 v11, 0xc3000000, v142
	global_store_dwordx4 v251, v[8:11], s[76:77]
	v_pk_add_f32 v[12:13], v[98:99], v[80:81]
	v_pk_add_f32 v[14:15], v[100:101], v[82:83]
	v_fmac_f32_e32 v12, 0xc3000000, v142
	v_fmac_f32_e32 v13, 0xc3000000, v142
	v_fmac_f32_e32 v14, 0xc3000000, v142
	v_fmac_f32_e32 v15, 0xc3000000, v142
	global_store_dwordx4 v251, v[12:15], s[76:77] offset:16
	v_pk_add_f32 v[16:17], v[94:95], v[76:77]
	v_pk_add_f32 v[18:19], v[96:97], v[78:79]
	v_fmac_f32_e32 v16, 0xc3000000, v142
	v_fmac_f32_e32 v17, 0xc3000000, v142
	v_fmac_f32_e32 v18, 0xc3000000, v142
	v_fmac_f32_e32 v19, 0xc3000000, v142
	global_store_dwordx4 v251, v[16:19], s[76:77] offset:32
	v_pk_add_f32 v[20:21], v[90:91], v[72:73]
	v_pk_add_f32 v[22:23], v[92:93], v[74:75]
	v_fmac_f32_e32 v20, 0xc3000000, v142
	v_fmac_f32_e32 v21, 0xc3000000, v142
	v_fmac_f32_e32 v22, 0xc3000000, v142
	v_fmac_f32_e32 v23, 0xc3000000, v142
	global_store_dwordx4 v251, v[20:23], s[76:77] offset:48
	s_add_i32 s25, s25, 1
	s_cmp_lt_u32 s25, 4
	s_cbranch_scc1 .Lxp_out
	s_waitcnt vmcnt(0)
	s_add_i32 s23, s23, 1
	s_cmp_lt_u32 s23, 8
	s_cbranch_scc1 .Lxp_sweep
	s_cmp_eq_u32 s82, 1
	s_cbranch_scc0 .Lxp_end
	v_bfrev_b32_e32 v245, 1
	s_mov_b64 exec, 1
	global_store_dword v[246:247], v245, off
	s_mov_b64 exec, -1
.Lxp_end:
	s_branch .LBB0_352

